# P3 causal conv: the 24 tap loads of an item (4 taps x q,k,v) are issued together up front instead of one dependent load-wait round trip per tap
# speedup vs baseline: 1.0194x; 1.0079x over previous
.LBB0_289:
	s_or_b64 exec, exec, s[4:5]
	v_lshlrev_b32_e32 v1, 4, v77
	v_and_b32_e32 v24, 0x70, v1
	v_lshlrev_b32_e32 v4, 1, v24
	v_ashrrev_i32_e32 v78, 3, v77
	v_lshl_or_b32 v22, s14, 8, v4
	v_add_u32_e32 v25, v0, v78
	s_lshl_b32 s12, s66, 12
	v_lshl_add_u64 v[32:33], s[22:23], 0, v[22:23]
	v_mov_b32_e32 v22, v23
	v_lshl_add_u32 v5, v24, 2, s77
	v_lshl_add_u64 v[34:35], v[32:33], 0, s[40:41]
	v_cmp_lt_i32_e64 s[0:1], 2, v25
	v_add3_u32 v0, v25, s12, -3
	v_mov_b64_e32 v[26:27], v[22:23]
	v_mov_b64_e32 v[18:19], v[22:23]
	v_mov_b64_e32 v[14:15], v[22:23]
	v_mov_b64_e32 v[10:11], v[22:23]
	v_mov_b64_e32 v[16:17], v[22:23]
	v_mov_b64_e32 v[12:13], v[22:23]
	v_mov_b64_e32 v[8:9], v[22:23]
	v_mov_b64_e32 v[6:7], v[22:23]
	v_mov_b32_e32 v89, 0
	v_add_u32_e32 v88, -3, v25
	v_max_i32_e32 v88, 0, v88
	v_add_u32_e32 v88, s12, v88
	v_lshlrev_b64 v[80:81], 13, v[88:89]
	v_lshl_add_u64 v[80:81], v[34:35], 0, v[80:81]
	v_add_u32_e32 v88, -2, v25
	v_max_i32_e32 v88, 0, v88
	v_add_u32_e32 v88, s12, v88
	v_lshlrev_b64 v[82:83], 13, v[88:89]
	v_lshl_add_u64 v[82:83], v[34:35], 0, v[82:83]
	v_add_u32_e32 v88, -1, v25
	v_max_i32_e32 v88, 0, v88
	v_add_u32_e32 v88, s12, v88
	v_lshlrev_b64 v[84:85], 13, v[88:89]
	v_lshl_add_u64 v[84:85], v[34:35], 0, v[84:85]
	v_add_u32_e32 v88, s12, v25
	v_lshlrev_b64 v[86:87], 13, v[88:89]
	v_lshl_add_u64 v[86:87], v[34:35], 0, v[86:87]
	global_load_dwordx4 v[144:147], v[80:81], off
	global_load_dwordx4 v[148:151], v[80:81], off offset:16
	global_load_dwordx4 v[152:155], v[82:83], off
	global_load_dwordx4 v[156:159], v[82:83], off offset:16
	global_load_dwordx4 v[160:163], v[84:85], off
	global_load_dwordx4 v[164:167], v[84:85], off offset:16
	global_load_dwordx4 v[168:171], v[86:87], off
	global_load_dwordx4 v[172:175], v[86:87], off offset:16
	global_load_dwordx4 v[176:179], v[80:81], off offset:1024
	global_load_dwordx4 v[180:183], v[80:81], off offset:1040
	global_load_dwordx4 v[184:187], v[82:83], off offset:1024
	global_load_dwordx4 v[188:191], v[82:83], off offset:1040
	global_load_dwordx4 v[192:195], v[84:85], off offset:1024
	global_load_dwordx4 v[196:199], v[84:85], off offset:1040
	global_load_dwordx4 v[200:203], v[86:87], off offset:1024
	global_load_dwordx4 v[204:207], v[86:87], off offset:1040
	global_load_dwordx4 v[208:211], v[80:81], off offset:2048
	global_load_dwordx4 v[212:215], v[80:81], off offset:2064
	global_load_dwordx4 v[216:219], v[82:83], off offset:2048
	global_load_dwordx4 v[220:223], v[82:83], off offset:2064
	global_load_dwordx4 v[224:227], v[84:85], off offset:2048
	global_load_dwordx4 v[228:231], v[84:85], off offset:2064
	global_load_dwordx4 v[232:235], v[86:87], off offset:2048
	global_load_dwordx4 v[236:239], v[86:87], off offset:2064
	s_and_saveexec_b64 s[4:5], s[0:1]
	s_cbranch_execz .LBB0_291
	v_ashrrev_i32_e32 v1, 31, v0
	v_lshlrev_b64 v[2:3], 13, v[0:1]
	v_lshl_add_u64 v[2:3], v[34:35], 0, v[2:3]
	s_waitcnt vmcnt(22)
	v_mov_b32_e32 v6, v144
	v_mov_b32_e32 v7, v145
	v_mov_b32_e32 v8, v146
	v_mov_b32_e32 v9, v147
	v_mov_b32_e32 v10, v148
	v_mov_b32_e32 v11, v149
	v_mov_b32_e32 v12, v150
	v_mov_b32_e32 v13, v151
	ds_read_b128 v[14:17], v5
	ds_read_b128 v[26:29], v5 offset:16
	ds_read_b128 v[36:39], v5 offset:32
	ds_read_b128 v[40:43], v5 offset:48
	s_nop 0
	v_lshlrev_b32_e32 v2, 16, v6
	v_and_b32_e32 v3, 0xffff0000, v6
	v_lshlrev_b32_e32 v6, 16, v7
	v_and_b32_e32 v7, 0xffff0000, v7
	v_lshlrev_b32_e32 v18, 16, v8
	v_and_b32_e32 v19, 0xffff0000, v8
	v_lshlrev_b32_e32 v8, 16, v9
	v_and_b32_e32 v9, 0xffff0000, v9
	s_nop 0
	v_lshlrev_b32_e32 v30, 16, v10
	v_and_b32_e32 v31, 0xffff0000, v10
	v_lshlrev_b32_e32 v44, 16, v11
	v_and_b32_e32 v45, 0xffff0000, v11
	v_lshlrev_b32_e32 v46, 16, v12
	v_and_b32_e32 v47, 0xffff0000, v12
	v_lshlrev_b32_e32 v48, 16, v13
	v_and_b32_e32 v49, 0xffff0000, v13
	s_waitcnt lgkmcnt(3)
	v_pk_fma_f32 v[10:11], v[14:15], v[2:3], 0 op_sel_hi:[1,1,0]
	v_pk_fma_f32 v[14:15], v[16:17], v[6:7], 0 op_sel_hi:[1,1,0]
	s_waitcnt lgkmcnt(2)
	v_pk_fma_f32 v[6:7], v[26:27], v[18:19], 0 op_sel_hi:[1,1,0]
	v_pk_fma_f32 v[8:9], v[28:29], v[8:9], 0 op_sel_hi:[1,1,0]
	s_waitcnt lgkmcnt(1)
	v_pk_fma_f32 v[18:19], v[36:37], v[30:31], 0 op_sel_hi:[1,1,0]
	v_pk_fma_f32 v[26:27], v[38:39], v[44:45], 0 op_sel_hi:[1,1,0]
	s_waitcnt lgkmcnt(0)
	v_pk_fma_f32 v[12:13], v[40:41], v[46:47], 0 op_sel_hi:[1,1,0]
	v_pk_fma_f32 v[16:17], v[42:43], v[48:49], 0 op_sel_hi:[1,1,0]
.LBB0_291:
	s_or_b64 exec, exec, s[4:5]
	v_cmp_lt_i32_e64 s[4:5], 1, v25
	v_add3_u32 v2, v25, s12, -2
	s_and_saveexec_b64 s[6:7], s[4:5]
	s_cbranch_execz .LBB0_293
	v_ashrrev_i32_e32 v3, 31, v2
	v_lshlrev_b64 v[28:29], 13, v[2:3]
	v_lshl_add_u64 v[36:37], v[34:35], 0, v[28:29]
	s_waitcnt vmcnt(20)
	v_mov_b32_e32 v28, v152
	v_mov_b32_e32 v29, v153
	v_mov_b32_e32 v30, v154
	v_mov_b32_e32 v31, v155
	s_nop 0
	v_mov_b32_e32 v36, v156
	v_mov_b32_e32 v37, v157
	v_mov_b32_e32 v38, v158
	v_mov_b32_e32 v39, v159
	ds_read_b128 v[40:43], v5 offset:512
	ds_read_b128 v[44:47], v5 offset:528
	ds_read_b128 v[48:51], v5 offset:544
	ds_read_b128 v[80:83], v5 offset:560
	s_nop 0
	v_lshlrev_b32_e32 v84, 16, v28
	v_and_b32_e32 v85, 0xffff0000, v28
	v_lshlrev_b32_e32 v28, 16, v29
	v_and_b32_e32 v29, 0xffff0000, v29
	v_lshlrev_b32_e32 v86, 16, v30
	v_and_b32_e32 v87, 0xffff0000, v30
	v_lshlrev_b32_e32 v30, 16, v31
	v_and_b32_e32 v31, 0xffff0000, v31
	s_nop 0
	v_lshlrev_b32_e32 v88, 16, v36
	v_and_b32_e32 v89, 0xffff0000, v36
	v_lshlrev_b32_e32 v36, 16, v37
	v_and_b32_e32 v37, 0xffff0000, v37
	v_lshlrev_b32_e32 v90, 16, v38
	v_and_b32_e32 v91, 0xffff0000, v38
	v_lshlrev_b32_e32 v38, 16, v39
	v_and_b32_e32 v39, 0xffff0000, v39
	s_waitcnt lgkmcnt(3)
	v_pk_fma_f32 v[10:11], v[40:41], v[84:85], v[10:11]
	v_pk_fma_f32 v[14:15], v[42:43], v[28:29], v[14:15]
	s_waitcnt lgkmcnt(2)
	v_pk_fma_f32 v[6:7], v[44:45], v[86:87], v[6:7]
	v_pk_fma_f32 v[8:9], v[46:47], v[30:31], v[8:9]
	s_waitcnt lgkmcnt(1)
	v_pk_fma_f32 v[18:19], v[48:49], v[88:89], v[18:19]
	v_pk_fma_f32 v[26:27], v[50:51], v[36:37], v[26:27]
	s_waitcnt lgkmcnt(0)
	v_pk_fma_f32 v[12:13], v[80:81], v[90:91], v[12:13]
	v_pk_fma_f32 v[16:17], v[82:83], v[38:39], v[16:17]
.LBB0_293:
	s_or_b64 exec, exec, s[6:7]
	v_cmp_lt_i32_e64 s[6:7], 0, v25
	v_add3_u32 v28, v25, s12, -1
	s_and_saveexec_b64 s[8:9], s[6:7]
	s_cbranch_execz .LBB0_295
	v_ashrrev_i32_e32 v29, 31, v28
	v_lshlrev_b64 v[30:31], 13, v[28:29]
	v_lshl_add_u64 v[30:31], v[34:35], 0, v[30:31]
	s_waitcnt vmcnt(18)
	v_mov_b32_e32 v36, v160
	v_mov_b32_e32 v37, v161
	v_mov_b32_e32 v38, v162
	v_mov_b32_e32 v39, v163
	v_mov_b32_e32 v40, v164
	v_mov_b32_e32 v41, v165
	v_mov_b32_e32 v42, v166
	v_mov_b32_e32 v43, v167
	ds_read_b128 v[44:47], v5 offset:1024
	ds_read_b128 v[48:51], v5 offset:1040
	ds_read_b128 v[80:83], v5 offset:1056
	ds_read_b128 v[84:87], v5 offset:1072
	s_nop 0
	v_lshlrev_b32_e32 v30, 16, v36
	v_and_b32_e32 v31, 0xffff0000, v36
	v_lshlrev_b32_e32 v36, 16, v37
	v_and_b32_e32 v37, 0xffff0000, v37
	v_lshlrev_b32_e32 v88, 16, v38
	v_and_b32_e32 v89, 0xffff0000, v38
	v_lshlrev_b32_e32 v38, 16, v39
	v_and_b32_e32 v39, 0xffff0000, v39
	s_nop 0
	v_lshlrev_b32_e32 v90, 16, v40
	v_and_b32_e32 v91, 0xffff0000, v40
	v_lshlrev_b32_e32 v40, 16, v41
	v_and_b32_e32 v41, 0xffff0000, v41
	v_lshlrev_b32_e32 v92, 16, v42
	v_and_b32_e32 v93, 0xffff0000, v42
	v_lshlrev_b32_e32 v42, 16, v43
	v_and_b32_e32 v43, 0xffff0000, v43
	s_waitcnt lgkmcnt(3)
	v_pk_fma_f32 v[10:11], v[44:45], v[30:31], v[10:11]
	v_pk_fma_f32 v[14:15], v[46:47], v[36:37], v[14:15]
	s_waitcnt lgkmcnt(2)
	v_pk_fma_f32 v[6:7], v[48:49], v[88:89], v[6:7]
	v_pk_fma_f32 v[8:9], v[50:51], v[38:39], v[8:9]
	s_waitcnt lgkmcnt(1)
	v_pk_fma_f32 v[18:19], v[80:81], v[90:91], v[18:19]
	v_pk_fma_f32 v[26:27], v[82:83], v[40:41], v[26:27]
	s_waitcnt lgkmcnt(0)
	v_pk_fma_f32 v[12:13], v[84:85], v[92:93], v[12:13]
	v_pk_fma_f32 v[16:17], v[86:87], v[42:43], v[16:17]
.LBB0_295:
	s_or_b64 exec, exec, s[8:9]
	v_add_u32_e32 v30, s12, v25
	v_cmp_lt_i32_e64 s[8:9], -1, v25
	v_ashrrev_i32_e32 v31, 31, v30
	s_and_saveexec_b64 s[12:13], s[8:9]
	s_cbranch_execz .LBB0_297
	v_lshlrev_b64 v[36:37], 13, v[30:31]
	v_lshl_add_u64 v[38:39], v[34:35], 0, v[36:37]
	s_waitcnt vmcnt(16)
	v_mov_b32_e32 v34, v168
	v_mov_b32_e32 v35, v169
	v_mov_b32_e32 v36, v170
	v_mov_b32_e32 v37, v171
	s_nop 0
	v_mov_b32_e32 v38, v172
	v_mov_b32_e32 v39, v173
	v_mov_b32_e32 v40, v174
	v_mov_b32_e32 v41, v175
	ds_read_b128 v[42:45], v5 offset:1536
	ds_read_b128 v[46:49], v5 offset:1552
	ds_read_b128 v[80:83], v5 offset:1568
	ds_read_b128 v[84:87], v5 offset:1584
	s_nop 0
	v_lshlrev_b32_e32 v50, 16, v34
	v_and_b32_e32 v51, 0xffff0000, v34
	v_lshlrev_b32_e32 v34, 16, v35
	v_and_b32_e32 v35, 0xffff0000, v35
	v_lshlrev_b32_e32 v88, 16, v36
	v_and_b32_e32 v89, 0xffff0000, v36
	v_lshlrev_b32_e32 v36, 16, v37
	v_and_b32_e32 v37, 0xffff0000, v37
	s_nop 0
	v_lshlrev_b32_e32 v90, 16, v38
	v_and_b32_e32 v91, 0xffff0000, v38
	v_lshlrev_b32_e32 v38, 16, v39
	v_and_b32_e32 v39, 0xffff0000, v39
	v_lshlrev_b32_e32 v92, 16, v40
	v_and_b32_e32 v93, 0xffff0000, v40
	v_lshlrev_b32_e32 v40, 16, v41
	v_and_b32_e32 v41, 0xffff0000, v41
	s_waitcnt lgkmcnt(3)
	v_pk_fma_f32 v[10:11], v[42:43], v[50:51], v[10:11]
	v_pk_fma_f32 v[14:15], v[44:45], v[34:35], v[14:15]
	s_waitcnt lgkmcnt(2)
	v_pk_fma_f32 v[6:7], v[46:47], v[88:89], v[6:7]
	v_pk_fma_f32 v[8:9], v[48:49], v[36:37], v[8:9]
	s_waitcnt lgkmcnt(1)
	v_pk_fma_f32 v[18:19], v[80:81], v[90:91], v[18:19]
	v_pk_fma_f32 v[26:27], v[82:83], v[38:39], v[26:27]
	s_waitcnt lgkmcnt(0)
	v_pk_fma_f32 v[12:13], v[84:85], v[92:93], v[12:13]
	v_pk_fma_f32 v[16:17], v[86:87], v[40:41], v[16:17]

.LBB0_301:
	v_lshlrev_b64 v[80:81], 13, v[30:31]
	v_lshl_add_u64 v[50:51], v[50:51], 0, v[80:81]
	s_waitcnt vmcnt(8)
	v_mov_b32_e32 v80, v200
	v_mov_b32_e32 v81, v201
	v_mov_b32_e32 v82, v202
	v_mov_b32_e32 v83, v203
	v_mov_b32_e32 v84, v204
	v_mov_b32_e32 v85, v205
	v_mov_b32_e32 v86, v206
	v_mov_b32_e32 v87, v207
	ds_read_b128 v[88:91], v25 offset:1536
	ds_read_b128 v[92:95], v25 offset:1552
	ds_read_b128 v[96:99], v25 offset:1568
	ds_read_b128 v[100:103], v25 offset:1584
	s_nop 0
	v_and_b32_e32 v51, 0xffff0000, v80
	v_lshlrev_b32_e32 v50, 16, v80
	v_and_b32_e32 v105, 0xffff0000, v81
	v_lshlrev_b32_e32 v104, 16, v81
	v_and_b32_e32 v81, 0xffff0000, v82
	v_lshlrev_b32_e32 v80, 16, v82
	v_and_b32_e32 v107, 0xffff0000, v83
	v_lshlrev_b32_e32 v106, 16, v83
	s_nop 0
	v_and_b32_e32 v83, 0xffff0000, v84
	v_lshlrev_b32_e32 v82, 16, v84
	v_and_b32_e32 v109, 0xffff0000, v85
	v_lshlrev_b32_e32 v108, 16, v85
	v_and_b32_e32 v85, 0xffff0000, v86
	v_lshlrev_b32_e32 v84, 16, v86
	v_and_b32_e32 v111, 0xffff0000, v87
	v_lshlrev_b32_e32 v110, 16, v87
	s_waitcnt lgkmcnt(3)
	v_pk_fma_f32 v[34:35], v[88:89], v[50:51], v[34:35]
	v_pk_fma_f32 v[36:37], v[90:91], v[104:105], v[36:37]
	s_waitcnt lgkmcnt(2)
	v_pk_fma_f32 v[38:39], v[92:93], v[80:81], v[38:39]
	v_pk_fma_f32 v[40:41], v[94:95], v[106:107], v[40:41]
	s_waitcnt lgkmcnt(1)
	v_pk_fma_f32 v[42:43], v[96:97], v[82:83], v[42:43]
	v_pk_fma_f32 v[44:45], v[98:99], v[108:109], v[44:45]
	s_waitcnt lgkmcnt(0)
	v_pk_fma_f32 v[46:47], v[100:101], v[84:85], v[46:47]
	v_pk_fma_f32 v[48:49], v[102:103], v[110:111], v[48:49]

.LBB0_306:
	v_lshlrev_b64 v[0:1], 13, v[30:31]
	v_lshl_add_u64 v[28:29], v[48:49], 0, v[0:1]
	s_waitcnt vmcnt(0)
	v_mov_b32_e32 v0, v232
	v_mov_b32_e32 v1, v233
	v_mov_b32_e32 v2, v234
	v_mov_b32_e32 v3, v235
	s_nop 0
	v_mov_b32_e32 v28, v236
	v_mov_b32_e32 v29, v237
	v_mov_b32_e32 v30, v238
	v_mov_b32_e32 v31, v239
	ds_read_b128 v[48:51], v25 offset:1536
	ds_read_b128 v[80:83], v25 offset:1552
	ds_read_b128 v[84:87], v25 offset:1568
	ds_read_b128 v[88:91], v25 offset:1584
	s_nop 0
	v_and_b32_e32 v93, 0xffff0000, v0
	v_lshlrev_b32_e32 v92, 16, v0
	v_and_b32_e32 v95, 0xffff0000, v1
	v_lshlrev_b32_e32 v94, 16, v1
	v_and_b32_e32 v1, 0xffff0000, v2
	v_lshlrev_b32_e32 v0, 16, v2
	v_and_b32_e32 v97, 0xffff0000, v3
	v_lshlrev_b32_e32 v96, 16, v3
	s_nop 0
	v_and_b32_e32 v3, 0xffff0000, v28
	v_lshlrev_b32_e32 v2, 16, v28
	v_and_b32_e32 v99, 0xffff0000, v29
	v_lshlrev_b32_e32 v98, 16, v29
	v_and_b32_e32 v29, 0xffff0000, v30
	v_lshlrev_b32_e32 v28, 16, v30
	v_and_b32_e32 v101, 0xffff0000, v31
	v_lshlrev_b32_e32 v100, 16, v31
	s_waitcnt lgkmcnt(3)
	v_pk_fma_f32 v[46:47], v[48:49], v[92:93], v[46:47]
	v_pk_fma_f32 v[44:45], v[50:51], v[94:95], v[44:45]
	s_waitcnt lgkmcnt(2)
	v_pk_fma_f32 v[42:43], v[80:81], v[0:1], v[42:43]
	v_pk_fma_f32 v[40:41], v[82:83], v[96:97], v[40:41]
	s_waitcnt lgkmcnt(1)
	v_pk_fma_f32 v[38:39], v[84:85], v[2:3], v[38:39]
	v_pk_fma_f32 v[36:37], v[86:87], v[98:99], v[36:37]
	s_waitcnt lgkmcnt(0)
	v_pk_fma_f32 v[32:33], v[88:89], v[28:29], v[32:33]
	v_pk_fma_f32 v[34:35], v[90:91], v[100:101], v[34:35]

.LBB0_343:
	v_ashrrev_i32_e32 v1, 31, v0
	v_lshlrev_b64 v[34:35], 13, v[0:1]
	v_lshl_add_u64 v[38:39], v[50:51], 0, v[34:35]
	s_waitcnt vmcnt(14)
	v_mov_b32_e32 v34, v176
	v_mov_b32_e32 v35, v177
	v_mov_b32_e32 v36, v178
	v_mov_b32_e32 v37, v179
	s_nop 0
	v_mov_b32_e32 v38, v180
	v_mov_b32_e32 v39, v181
	v_mov_b32_e32 v40, v182
	v_mov_b32_e32 v41, v183
	ds_read_b128 v[42:45], v25
	ds_read_b128 v[46:49], v25 offset:16
	ds_read_b128 v[80:83], v25 offset:32
	ds_read_b128 v[84:87], v25 offset:48
	s_nop 0
	v_and_b32_e32 v89, 0xffff0000, v34
	v_lshlrev_b32_e32 v88, 16, v34
	v_and_b32_e32 v91, 0xffff0000, v35
	v_lshlrev_b32_e32 v90, 16, v35
	v_and_b32_e32 v93, 0xffff0000, v36
	v_lshlrev_b32_e32 v92, 16, v36
	v_and_b32_e32 v95, 0xffff0000, v37
	v_lshlrev_b32_e32 v94, 16, v37
	s_nop 0
	v_and_b32_e32 v97, 0xffff0000, v38
	v_lshlrev_b32_e32 v96, 16, v38
	v_and_b32_e32 v99, 0xffff0000, v39
	v_lshlrev_b32_e32 v98, 16, v39
	v_and_b32_e32 v101, 0xffff0000, v40
	v_lshlrev_b32_e32 v100, 16, v40
	v_and_b32_e32 v103, 0xffff0000, v41
	v_lshlrev_b32_e32 v102, 16, v41
	s_waitcnt lgkmcnt(3)
	v_pk_fma_f32 v[34:35], v[42:43], v[88:89], 0 op_sel_hi:[1,1,0]
	v_pk_fma_f32 v[36:37], v[44:45], v[90:91], 0 op_sel_hi:[1,1,0]
	s_waitcnt lgkmcnt(2)
	v_pk_fma_f32 v[38:39], v[46:47], v[92:93], 0 op_sel_hi:[1,1,0]
	v_pk_fma_f32 v[40:41], v[48:49], v[94:95], 0 op_sel_hi:[1,1,0]
	s_waitcnt lgkmcnt(1)
	v_pk_fma_f32 v[42:43], v[80:81], v[96:97], 0 op_sel_hi:[1,1,0]
	v_pk_fma_f32 v[44:45], v[82:83], v[98:99], 0 op_sel_hi:[1,1,0]
	s_waitcnt lgkmcnt(0)
	v_pk_fma_f32 v[46:47], v[84:85], v[100:101], 0 op_sel_hi:[1,1,0]
	v_pk_fma_f32 v[48:49], v[86:87], v[102:103], 0 op_sel_hi:[1,1,0]
	s_or_b64 exec, exec, s[12:13]
	s_and_saveexec_b64 s[12:13], s[4:5]
	s_cbranch_execz .LBB0_299
.LBB0_344:
	v_ashrrev_i32_e32 v3, 31, v2
	v_lshlrev_b64 v[80:81], 13, v[2:3]
	v_lshl_add_u64 v[84:85], v[50:51], 0, v[80:81]
	s_waitcnt vmcnt(12)
	v_mov_b32_e32 v80, v184
	v_mov_b32_e32 v81, v185
	v_mov_b32_e32 v82, v186
	v_mov_b32_e32 v83, v187
	s_nop 0
	v_mov_b32_e32 v84, v188
	v_mov_b32_e32 v85, v189
	v_mov_b32_e32 v86, v190
	v_mov_b32_e32 v87, v191
	ds_read_b128 v[88:91], v25 offset:512
	ds_read_b128 v[92:95], v25 offset:528
	ds_read_b128 v[96:99], v25 offset:544
	ds_read_b128 v[100:103], v25 offset:560
	s_nop 0
	v_and_b32_e32 v105, 0xffff0000, v80
	v_lshlrev_b32_e32 v104, 16, v80
	v_and_b32_e32 v107, 0xffff0000, v81
	v_lshlrev_b32_e32 v106, 16, v81
	v_and_b32_e32 v81, 0xffff0000, v82
	v_lshlrev_b32_e32 v80, 16, v82
	v_and_b32_e32 v109, 0xffff0000, v83
	v_lshlrev_b32_e32 v108, 16, v83
	s_nop 0
	v_and_b32_e32 v83, 0xffff0000, v84
	v_lshlrev_b32_e32 v82, 16, v84
	v_and_b32_e32 v111, 0xffff0000, v85
	v_lshlrev_b32_e32 v110, 16, v85
	v_and_b32_e32 v85, 0xffff0000, v86
	v_lshlrev_b32_e32 v84, 16, v86
	v_and_b32_e32 v113, 0xffff0000, v87
	v_lshlrev_b32_e32 v112, 16, v87
	s_waitcnt lgkmcnt(3)
	v_pk_fma_f32 v[34:35], v[88:89], v[104:105], v[34:35]
	v_pk_fma_f32 v[36:37], v[90:91], v[106:107], v[36:37]
	s_waitcnt lgkmcnt(2)
	v_pk_fma_f32 v[38:39], v[92:93], v[80:81], v[38:39]
	v_pk_fma_f32 v[40:41], v[94:95], v[108:109], v[40:41]
	s_waitcnt lgkmcnt(1)
	v_pk_fma_f32 v[42:43], v[96:97], v[82:83], v[42:43]
	v_pk_fma_f32 v[44:45], v[98:99], v[110:111], v[44:45]
	s_waitcnt lgkmcnt(0)
	v_pk_fma_f32 v[46:47], v[100:101], v[84:85], v[46:47]
	v_pk_fma_f32 v[48:49], v[102:103], v[112:113], v[48:49]
	s_or_b64 exec, exec, s[12:13]
	s_and_saveexec_b64 s[12:13], s[6:7]
	s_cbranch_execz .LBB0_300
.LBB0_345:
	v_ashrrev_i32_e32 v29, 31, v28
	v_lshlrev_b64 v[80:81], 13, v[28:29]
	v_lshl_add_u64 v[84:85], v[50:51], 0, v[80:81]
	s_waitcnt vmcnt(10)
	v_mov_b32_e32 v80, v192
	v_mov_b32_e32 v81, v193
	v_mov_b32_e32 v82, v194
	v_mov_b32_e32 v83, v195
	s_nop 0
	v_mov_b32_e32 v84, v196
	v_mov_b32_e32 v85, v197
	v_mov_b32_e32 v86, v198
	v_mov_b32_e32 v87, v199
	ds_read_b128 v[88:91], v25 offset:1024
	ds_read_b128 v[92:95], v25 offset:1040
	ds_read_b128 v[96:99], v25 offset:1056
	ds_read_b128 v[100:103], v25 offset:1072
	s_nop 0
	v_and_b32_e32 v105, 0xffff0000, v80
	v_lshlrev_b32_e32 v104, 16, v80
	v_and_b32_e32 v107, 0xffff0000, v81
	v_lshlrev_b32_e32 v106, 16, v81
	v_and_b32_e32 v81, 0xffff0000, v82
	v_lshlrev_b32_e32 v80, 16, v82
	v_and_b32_e32 v109, 0xffff0000, v83
	v_lshlrev_b32_e32 v108, 16, v83
	s_nop 0
	v_and_b32_e32 v83, 0xffff0000, v84
	v_lshlrev_b32_e32 v82, 16, v84
	v_and_b32_e32 v111, 0xffff0000, v85
	v_lshlrev_b32_e32 v110, 16, v85
	v_and_b32_e32 v85, 0xffff0000, v86
	v_lshlrev_b32_e32 v84, 16, v86
	v_and_b32_e32 v113, 0xffff0000, v87
	v_lshlrev_b32_e32 v112, 16, v87
	s_waitcnt lgkmcnt(3)
	v_pk_fma_f32 v[34:35], v[88:89], v[104:105], v[34:35]
	v_pk_fma_f32 v[36:37], v[90:91], v[106:107], v[36:37]
	s_waitcnt lgkmcnt(2)
	v_pk_fma_f32 v[38:39], v[92:93], v[80:81], v[38:39]
	v_pk_fma_f32 v[40:41], v[94:95], v[108:109], v[40:41]
	s_waitcnt lgkmcnt(1)
	v_pk_fma_f32 v[42:43], v[96:97], v[82:83], v[42:43]
	v_pk_fma_f32 v[44:45], v[98:99], v[110:111], v[44:45]
	s_waitcnt lgkmcnt(0)
	v_pk_fma_f32 v[46:47], v[100:101], v[84:85], v[46:47]
	v_pk_fma_f32 v[48:49], v[102:103], v[112:113], v[48:49]
	s_or_b64 exec, exec, s[12:13]
	s_and_saveexec_b64 s[12:13], s[8:9]
	s_cbranch_execnz .LBB0_301
	s_branch .LBB0_302
.LBB0_346:
	v_ashrrev_i32_e32 v1, 31, v0
	v_lshlrev_b64 v[0:1], 13, v[0:1]
	v_lshl_add_u64 v[0:1], v[48:49], 0, v[0:1]
	s_waitcnt vmcnt(6)
	v_mov_b32_e32 v32, v208
	v_mov_b32_e32 v33, v209
	v_mov_b32_e32 v34, v210
	v_mov_b32_e32 v35, v211
	v_mov_b32_e32 v36, v212
	v_mov_b32_e32 v37, v213
	v_mov_b32_e32 v38, v214
	v_mov_b32_e32 v39, v215
	ds_read_b128 v[40:43], v25
	ds_read_b128 v[80:83], v25 offset:16
	ds_read_b128 v[84:87], v25 offset:32
	ds_read_b128 v[88:91], v25 offset:48
	s_nop 0
	v_and_b32_e32 v1, 0xffff0000, v32
	v_lshlrev_b32_e32 v0, 16, v32
	v_and_b32_e32 v45, 0xffff0000, v33
	v_lshlrev_b32_e32 v44, 16, v33
	v_and_b32_e32 v33, 0xffff0000, v34
	v_lshlrev_b32_e32 v32, 16, v34
	v_and_b32_e32 v51, 0xffff0000, v35
	v_lshlrev_b32_e32 v50, 16, v35
	s_nop 0
	v_and_b32_e32 v35, 0xffff0000, v36
	v_lshlrev_b32_e32 v34, 16, v36
	v_and_b32_e32 v93, 0xffff0000, v37
	v_lshlrev_b32_e32 v92, 16, v37
	v_and_b32_e32 v95, 0xffff0000, v38
	v_lshlrev_b32_e32 v94, 16, v38
	v_and_b32_e32 v97, 0xffff0000, v39
	v_lshlrev_b32_e32 v96, 16, v39
	s_waitcnt lgkmcnt(3)
	v_pk_fma_f32 v[46:47], v[40:41], v[0:1], 0 op_sel_hi:[1,1,0]
	v_pk_fma_f32 v[44:45], v[42:43], v[44:45], 0 op_sel_hi:[1,1,0]
	s_waitcnt lgkmcnt(2)
	v_pk_fma_f32 v[42:43], v[80:81], v[32:33], 0 op_sel_hi:[1,1,0]
	v_pk_fma_f32 v[40:41], v[82:83], v[50:51], 0 op_sel_hi:[1,1,0]
	s_waitcnt lgkmcnt(1)
	v_pk_fma_f32 v[38:39], v[84:85], v[34:35], 0 op_sel_hi:[1,1,0]
	v_pk_fma_f32 v[36:37], v[86:87], v[92:93], 0 op_sel_hi:[1,1,0]
	s_waitcnt lgkmcnt(0)
	v_pk_fma_f32 v[32:33], v[88:89], v[94:95], 0 op_sel_hi:[1,1,0]
	v_pk_fma_f32 v[34:35], v[90:91], v[96:97], 0 op_sel_hi:[1,1,0]
	s_or_b64 exec, exec, s[12:13]
	s_and_saveexec_b64 s[0:1], s[4:5]
	s_cbranch_execz .LBB0_304
.LBB0_347:
	v_ashrrev_i32_e32 v3, 31, v2
	v_lshlrev_b64 v[0:1], 13, v[2:3]
	v_lshl_add_u64 v[50:51], v[48:49], 0, v[0:1]
	s_waitcnt vmcnt(4)
	v_mov_b32_e32 v0, v216
	v_mov_b32_e32 v1, v217
	v_mov_b32_e32 v2, v218
	v_mov_b32_e32 v3, v219
	v_mov_b32_e32 v80, v220
	v_mov_b32_e32 v81, v221
	v_mov_b32_e32 v82, v222
	v_mov_b32_e32 v83, v223
	ds_read_b128 v[84:87], v25 offset:512
	ds_read_b128 v[88:91], v25 offset:528
	ds_read_b128 v[92:95], v25 offset:544
	ds_read_b128 v[96:99], v25 offset:560
	s_nop 0
	v_and_b32_e32 v51, 0xffff0000, v0
	v_lshlrev_b32_e32 v50, 16, v0
	v_and_b32_e32 v101, 0xffff0000, v1
	v_lshlrev_b32_e32 v100, 16, v1
	v_and_b32_e32 v1, 0xffff0000, v2
	v_lshlrev_b32_e32 v0, 16, v2
	v_and_b32_e32 v103, 0xffff0000, v3
	v_lshlrev_b32_e32 v102, 16, v3
	s_nop 0
	v_and_b32_e32 v3, 0xffff0000, v80
	v_lshlrev_b32_e32 v2, 16, v80
	v_and_b32_e32 v105, 0xffff0000, v81
	v_lshlrev_b32_e32 v104, 16, v81
	v_and_b32_e32 v81, 0xffff0000, v82
	v_lshlrev_b32_e32 v80, 16, v82
	v_and_b32_e32 v107, 0xffff0000, v83
	v_lshlrev_b32_e32 v106, 16, v83
	s_waitcnt lgkmcnt(3)
	v_pk_fma_f32 v[46:47], v[84:85], v[50:51], v[46:47]
	v_pk_fma_f32 v[44:45], v[86:87], v[100:101], v[44:45]
	s_waitcnt lgkmcnt(2)
	v_pk_fma_f32 v[42:43], v[88:89], v[0:1], v[42:43]
	v_pk_fma_f32 v[40:41], v[90:91], v[102:103], v[40:41]
	s_waitcnt lgkmcnt(1)
	v_pk_fma_f32 v[38:39], v[92:93], v[2:3], v[38:39]
	v_pk_fma_f32 v[36:37], v[94:95], v[104:105], v[36:37]
	s_waitcnt lgkmcnt(0)
	v_pk_fma_f32 v[32:33], v[96:97], v[80:81], v[32:33]
	v_pk_fma_f32 v[34:35], v[98:99], v[106:107], v[34:35]
	s_or_b64 exec, exec, s[0:1]
	s_and_saveexec_b64 s[0:1], s[6:7]
	s_cbranch_execz .LBB0_305
.LBB0_348:
	v_ashrrev_i32_e32 v29, 31, v28
	v_lshlrev_b64 v[0:1], 13, v[28:29]
	v_lshl_add_u64 v[28:29], v[48:49], 0, v[0:1]
	s_waitcnt vmcnt(2)
	v_mov_b32_e32 v0, v224
	v_mov_b32_e32 v1, v225
	v_mov_b32_e32 v2, v226
	v_mov_b32_e32 v3, v227
	v_mov_b32_e32 v80, v228
	v_mov_b32_e32 v81, v229
	v_mov_b32_e32 v82, v230
	v_mov_b32_e32 v83, v231
	ds_read_b128 v[84:87], v25 offset:1024
	ds_read_b128 v[88:91], v25 offset:1040
	ds_read_b128 v[92:95], v25 offset:1056
	ds_read_b128 v[96:99], v25 offset:1072
	s_nop 0
	v_and_b32_e32 v29, 0xffff0000, v0
	v_lshlrev_b32_e32 v28, 16, v0
	v_and_b32_e32 v51, 0xffff0000, v1
	v_lshlrev_b32_e32 v50, 16, v1
	v_and_b32_e32 v1, 0xffff0000, v2
	v_lshlrev_b32_e32 v0, 16, v2
	v_and_b32_e32 v101, 0xffff0000, v3
	v_lshlrev_b32_e32 v100, 16, v3
	s_nop 0
	v_and_b32_e32 v3, 0xffff0000, v80
	v_lshlrev_b32_e32 v2, 16, v80
	v_and_b32_e32 v103, 0xffff0000, v81
	v_lshlrev_b32_e32 v102, 16, v81
	v_and_b32_e32 v81, 0xffff0000, v82
	v_lshlrev_b32_e32 v80, 16, v82
	v_and_b32_e32 v105, 0xffff0000, v83
	v_lshlrev_b32_e32 v104, 16, v83
	s_waitcnt lgkmcnt(3)
	v_pk_fma_f32 v[46:47], v[84:85], v[28:29], v[46:47]
	v_pk_fma_f32 v[44:45], v[86:87], v[50:51], v[44:45]
	s_waitcnt lgkmcnt(2)
	v_pk_fma_f32 v[42:43], v[88:89], v[0:1], v[42:43]
	v_pk_fma_f32 v[40:41], v[90:91], v[100:101], v[40:41]
	s_waitcnt lgkmcnt(1)
	v_pk_fma_f32 v[38:39], v[92:93], v[2:3], v[38:39]
	v_pk_fma_f32 v[36:37], v[94:95], v[102:103], v[36:37]
	s_waitcnt lgkmcnt(0)
	v_pk_fma_f32 v[32:33], v[96:97], v[80:81], v[32:33]
	v_pk_fma_f32 v[34:35], v[98:99], v[104:105], v[34:35]
	s_or_b64 exec, exec, s[0:1]
	s_and_saveexec_b64 s[0:1], s[8:9]
	s_cbranch_execnz .LBB0_306
	s_branch .LBB0_307
